# plus batched RES sample-row split-K loads and cvt_pk rounding in SSD state/y stores
# baseline (speedup 1.0000x reference)
; template <int EPI>
; __device__ __forceinline__ void gemm_phase(KP P, const bfu* __restrict__ A, const bfu* __restrict__ Bt, int K, int ntn, char* smem, const int wv) {
;     ...
;       for (int ks = 0; ks < kw; ks += 32) {
;         bf16x8 af[2], bf[4];
; #pragma unroll
;         for (int rt = 0; rt < 2; ++rt) af[rt] = *(const bf16x8*)(ap + (size_t)rt * 16 * K + ks);
; #pragma unroll
;         for (int ct = 0; ct < 4; ++ct) bf[ct] = *(const bf16x8*)(bp + (size_t)ct * 16 * K + ks);
; #pragma unroll
;         for (int rt = 0; rt < 2; ++rt)
; #pragma unroll
;           for (int ct = 0; ct < 4; ++ct) pacc[rt][ct] = mfma16(af[rt], bf[ct], pacc[rt][ct]);
;       }
.LBB0_291:
	v_lshl_add_u64 v[62:63], v[44:45], 0, s[10:11]
	v_lshl_add_u64 v[82:83], v[46:47], 0, s[10:11]
	v_lshl_add_u64 v[66:67], v[48:49], 0, s[10:11]
	v_lshl_add_u64 v[70:71], v[50:51], 0, s[10:11]
	v_lshl_add_u64 v[74:75], v[52:53], 0, s[10:11]
	v_lshl_add_u64 v[78:79], v[54:55], 0, s[10:11]
	global_load_dwordx4 v[84:87], v[62:63], off
	global_load_dwordx4 v[88:91], v[66:67], off
	global_load_dwordx4 v[92:95], v[70:71], off
	global_load_dwordx4 v[96:99], v[74:75], off
	global_load_dwordx4 v[100:103], v[78:79], off
	global_load_dwordx4 v[104:107], v[82:83], off
	s_add_i32 vcc_lo, s18, 32
	s_cmp_ge_u32 vcc_lo, s14
	s_cbranch_scc1 .Lsp_ld_done
	global_load_dwordx4 v[108:111], v[62:63], off offset:64
	global_load_dwordx4 v[112:115], v[66:67], off offset:64
	global_load_dwordx4 v[116:119], v[70:71], off offset:64
	global_load_dwordx4 v[120:123], v[74:75], off offset:64
	global_load_dwordx4 v[124:127], v[78:79], off offset:64
	global_load_dwordx4 v[128:131], v[82:83], off offset:64
	s_add_i32 vcc_lo, s18, 64
	s_cmp_ge_u32 vcc_lo, s14
	s_cbranch_scc1 .Lsp_ld_done
	global_load_dwordx4 v[180:183], v[62:63], off offset:128
	global_load_dwordx4 v[184:187], v[66:67], off offset:128
	global_load_dwordx4 v[188:191], v[70:71], off offset:128
	global_load_dwordx4 v[192:195], v[74:75], off offset:128
	global_load_dwordx4 v[196:199], v[78:79], off offset:128
	global_load_dwordx4 v[200:203], v[82:83], off offset:128
	s_add_i32 vcc_lo, s18, 96
	s_cmp_ge_u32 vcc_lo, s14
	s_cbranch_scc1 .Lsp_ld_done
	global_load_dwordx4 v[204:207], v[62:63], off offset:192
	global_load_dwordx4 v[208:211], v[66:67], off offset:192
	global_load_dwordx4 v[212:215], v[70:71], off offset:192
	global_load_dwordx4 v[216:219], v[74:75], off offset:192
	global_load_dwordx4 v[220:223], v[78:79], off offset:192
	global_load_dwordx4 v[224:227], v[82:83], off offset:192
.Lsp_ld_done:
	s_waitcnt vmcnt(0)
	v_mfma_f32_16x16x32_bf16 v[30:33], v[84:87], v[88:91], v[30:33]
	v_mfma_f32_16x16x32_bf16 v[26:29], v[84:87], v[92:95], v[26:29]
	v_mfma_f32_16x16x32_bf16 v[22:25], v[84:87], v[96:99], v[22:25]
	v_mfma_f32_16x16x32_bf16 v[18:21], v[84:87], v[100:103], v[18:21]
	v_mfma_f32_16x16x32_bf16 v[14:17], v[104:107], v[88:91], v[14:17]
	v_mfma_f32_16x16x32_bf16 v[10:13], v[104:107], v[92:95], v[10:13]
	v_mfma_f32_16x16x32_bf16 v[6:9], v[104:107], v[96:99], v[6:9]
	v_mfma_f32_16x16x32_bf16 v[2:5], v[104:107], v[100:103], v[2:5]
	s_add_i32 vcc_lo, s18, 32
	s_cmp_ge_u32 vcc_lo, s14
	s_cbranch_scc1 .Lsp_mm_done
	v_mfma_f32_16x16x32_bf16 v[30:33], v[108:111], v[112:115], v[30:33]
	v_mfma_f32_16x16x32_bf16 v[26:29], v[108:111], v[116:119], v[26:29]
	v_mfma_f32_16x16x32_bf16 v[22:25], v[108:111], v[120:123], v[22:25]
	v_mfma_f32_16x16x32_bf16 v[18:21], v[108:111], v[124:127], v[18:21]
	v_mfma_f32_16x16x32_bf16 v[14:17], v[128:131], v[112:115], v[14:17]
	v_mfma_f32_16x16x32_bf16 v[10:13], v[128:131], v[116:119], v[10:13]
	v_mfma_f32_16x16x32_bf16 v[6:9], v[128:131], v[120:123], v[6:9]
	v_mfma_f32_16x16x32_bf16 v[2:5], v[128:131], v[124:127], v[2:5]
	s_add_i32 vcc_lo, s18, 64
	s_cmp_ge_u32 vcc_lo, s14
	s_cbranch_scc1 .Lsp_mm_done
	v_mfma_f32_16x16x32_bf16 v[30:33], v[180:183], v[184:187], v[30:33]
	v_mfma_f32_16x16x32_bf16 v[26:29], v[180:183], v[188:191], v[26:29]
	v_mfma_f32_16x16x32_bf16 v[22:25], v[180:183], v[192:195], v[22:25]
	v_mfma_f32_16x16x32_bf16 v[18:21], v[180:183], v[196:199], v[18:21]
	v_mfma_f32_16x16x32_bf16 v[14:17], v[200:203], v[184:187], v[14:17]
	v_mfma_f32_16x16x32_bf16 v[10:13], v[200:203], v[188:191], v[10:13]
	v_mfma_f32_16x16x32_bf16 v[6:9], v[200:203], v[192:195], v[6:9]
	v_mfma_f32_16x16x32_bf16 v[2:5], v[200:203], v[196:199], v[2:5]
	s_add_i32 vcc_lo, s18, 96
	s_cmp_ge_u32 vcc_lo, s14
	s_cbranch_scc1 .Lsp_mm_done
	v_mfma_f32_16x16x32_bf16 v[30:33], v[204:207], v[208:211], v[30:33]
	v_mfma_f32_16x16x32_bf16 v[26:29], v[204:207], v[212:215], v[26:29]
	v_mfma_f32_16x16x32_bf16 v[22:25], v[204:207], v[216:219], v[22:25]
	v_mfma_f32_16x16x32_bf16 v[18:21], v[204:207], v[220:223], v[18:21]
	v_mfma_f32_16x16x32_bf16 v[14:17], v[224:227], v[208:211], v[14:17]
	v_mfma_f32_16x16x32_bf16 v[10:13], v[224:227], v[212:215], v[10:13]
	v_mfma_f32_16x16x32_bf16 v[6:9], v[224:227], v[216:219], v[6:9]
	v_mfma_f32_16x16x32_bf16 v[2:5], v[224:227], v[220:223], v[2:5]
; __device__ __forceinline__ float bf2f(bfu h) { return __uint_as_float(((unsigned)h) << 16); }
; template <int EPI>
; __device__ __forceinline__ void gemm_phase(KP P, const bfu* __restrict__ A, const bfu* __restrict__ Bt, int K, int ntn, char* smem, const int wv) {
;     ...
;       for (int ks = 0; ks < kw; ks += 32) {
;         bf16x8 af[2], bf[4];
; #pragma unroll
;         for (int rt = 0; rt < 2; ++rt) af[rt] = *(const bf16x8*)(ap + (size_t)rt * 16 * K + ks);
; #pragma unroll
;         for (int ct = 0; ct < 4; ++ct) bf[ct] = *(const bf16x8*)(bp + (size_t)ct * 16 * K + ks);
; #pragma unroll
;         for (int rt = 0; rt < 2; ++rt)
; #pragma unroll
;           for (int ct = 0; ct < 4; ++ct) pacc[rt][ct] = mfma16(af[rt], bf[ct], pacc[rt][ct]);
;       }
;       __syncthreads();
; #pragma unroll
;       for (int rt = 0; rt < 2; ++rt)
; #pragma unroll
;         for (int ct = 0; ct < 4; ++ct) *(f32x4*)(sRed + ((wid * 8 + rt * 4 + ct) * 64 + lane) * 4) = pacc[rt][ct];
;       __syncthreads();
;       {
;         f32x4 sum = {0.f, 0.f, 0.f, 0.f};
; #pragma unroll
;         for (int ww = 0; ww < 8; ++ww) sum += *(const f32x4*)(sRed + ((ww * 8 + wid) * 64 + lane) * 4);
;         const int col = cb * 64 + (wid & 3) * 16 + fr;
; #pragma unroll
;         for (int j = 0; j < 4; ++j) {
;           const int srow = rb * 32 + (wid >> 2) * 16 + fq * 4 + j;
;           bfu* op = (bfu*)(P->ws + WS_XR) + (size_t)(MP + srow) * D + col;
;           if (EPI == EPI_OUTPROJ) {
;             const float rs = ssd_rstd((const float*)(P->ws + WS_SSQ), MP + srow);
;             *op = f2bf(P->in[1][(size_t)srow * D + col] + rs * sum[j]);
;           } else {
;             *op = f2bf(bf2f(*op) + sum[j]);
;           }
;         }
;       }
.Lsp_mm_done:
	v_lshl_add_u64 v[44:45], 64, 2, v[44:45]
	v_lshl_add_u64 v[46:47], 64, 2, v[46:47]
	v_lshl_add_u64 v[48:49], 64, 2, v[48:49]
	v_lshl_add_u64 v[50:51], 64, 2, v[50:51]
	v_lshl_add_u64 v[52:53], 64, 2, v[52:53]
	v_lshl_add_u64 v[54:55], 64, 2, v[54:55]
	s_add_i32 s18, s18, 0x80
	s_cmp_ge_u32 s18, s14
	s_cbranch_scc0 .LBB0_291
	s_waitcnt lgkmcnt(0)
	s_barrier
	ds_write_b128 v59, v[30:33]
	ds_write_b128 v59, v[26:29] offset:1024
	ds_write_b128 v59, v[22:25] offset:2048
	ds_write_b128 v59, v[18:21] offset:3072
	ds_write_b128 v59, v[14:17] offset:4096
	ds_write_b128 v59, v[10:13] offset:5120
	ds_write_b128 v59, v[6:9] offset:6144
	ds_write_b128 v59, v[2:5] offset:7168
	s_waitcnt lgkmcnt(0)
	s_barrier
	ds_read_b128 v[2:5], v60
	s_lshl_b32 s18, s9, 1
	s_andn2_b32 s18, s18, 31
	v_or_b32_e32 v0, s17, v56
	v_lshlrev_b32_e32 v0, 1, v0
	s_waitcnt lgkmcnt(0)
	v_pk_add_f32 v[6:7], v[4:5], 0 op_sel_hi:[1,0]
	v_pk_add_f32 v[8:9], v[2:3], 0 op_sel_hi:[1,0]
	ds_read_b128 v[2:5], v60 offset:8192
	s_add_i32 s9, s9, s2
	s_add_i32 s8, s8, s16
	s_cmpk_gt_i32 s9, 0xff
	s_waitcnt lgkmcnt(0)
	v_pk_add_f32 v[6:7], v[6:7], v[4:5]
	v_pk_add_f32 v[8:9], v[8:9], v[2:3]
	ds_read_b128 v[2:5], v60 offset:16384
	s_waitcnt lgkmcnt(0)
	v_pk_add_f32 v[6:7], v[6:7], v[4:5]
	v_pk_add_f32 v[8:9], v[8:9], v[2:3]
	ds_read_b128 v[2:5], v60 offset:24576
	s_waitcnt lgkmcnt(0)
	v_pk_add_f32 v[6:7], v[6:7], v[4:5]
	v_pk_add_f32 v[8:9], v[8:9], v[2:3]
	ds_read_b128 v[2:5], v60 offset:32768
	s_waitcnt lgkmcnt(0)
	v_pk_add_f32 v[6:7], v[6:7], v[4:5]
	v_pk_add_f32 v[8:9], v[8:9], v[2:3]
	ds_read_b128 v[2:5], v60 offset:40960
	s_waitcnt lgkmcnt(0)
	v_pk_add_f32 v[6:7], v[6:7], v[4:5]
	v_pk_add_f32 v[8:9], v[8:9], v[2:3]
	ds_read_b128 v[2:5], v60 offset:49152
	s_waitcnt lgkmcnt(0)
	v_pk_add_f32 v[6:7], v[6:7], v[4:5]
	v_pk_add_f32 v[8:9], v[8:9], v[2:3]
	ds_read_b128 v[2:5], v60 offset:57344
	s_waitcnt lgkmcnt(0)
	v_pk_add_f32 v[4:5], v[6:7], v[4:5]
	v_add_u32_e32 v6, s18, v57
	v_ashrrev_i32_e32 v7, 31, v6
	v_pk_add_f32 v[2:3], v[8:9], v[2:3]
	v_lshl_add_u64 v[8:9], s[4:5], 0, v[0:1]
	v_lshlrev_b64 v[10:11], 11, v[6:7]
	v_lshl_add_u64 v[10:11], v[8:9], 0, v[10:11]
	global_load_ushort v0, v[10:11], off
	s_waitcnt vmcnt(0)
	v_lshlrev_b32_e32 v0, 16, v0
	v_add_f32_e32 v0, v2, v0
	v_bfe_u32 v2, v0, 16, 1
	v_add3_u32 v0, v0, v2, s96
	global_store_short_d16_hi v[10:11], v0, off
	v_or_b32_e32 v10, 1, v6
	v_ashrrev_i32_e32 v11, 31, v10
	v_lshlrev_b64 v[10:11], 11, v[10:11]
	v_lshl_add_u64 v[10:11], v[8:9], 0, v[10:11]
	global_load_ushort v0, v[10:11], off
	s_waitcnt vmcnt(0)
	v_lshlrev_b32_e32 v0, 16, v0
	v_add_f32_e32 v0, v3, v0
	v_bfe_u32 v2, v0, 16, 1
	v_add3_u32 v0, v0, v2, s96
	v_or_b32_e32 v2, 2, v6
	v_ashrrev_i32_e32 v3, 31, v2
	v_lshlrev_b64 v[2:3], 11, v[2:3]
	v_lshl_add_u64 v[2:3], v[8:9], 0, v[2:3]
	global_store_short_d16_hi v[10:11], v0, off
	global_load_ushort v0, v[2:3], off
	s_waitcnt vmcnt(0)
	v_lshlrev_b32_e32 v0, 16, v0
	v_add_f32_e32 v0, v4, v0
	v_bfe_u32 v4, v0, 16, 1
	v_add3_u32 v0, v0, v4, s96
	global_store_short_d16_hi v[2:3], v0, off
	v_or_b32_e32 v2, 3, v6
	v_ashrrev_i32_e32 v3, 31, v2
	v_lshlrev_b64 v[2:3], 11, v[2:3]
	v_lshl_add_u64 v[2:3], v[8:9], 0, v[2:3]
	global_load_ushort v0, v[2:3], off
	s_waitcnt vmcnt(0)
	v_lshlrev_b32_e32 v0, 16, v0
	v_add_f32_e32 v0, v5, v0
	v_bfe_u32 v4, v0, 16, 1
	v_add3_u32 v0, v0, v4, s96
	global_store_short_d16_hi v[2:3], v0, off
	s_cbranch_scc0 .LBB0_290

; __device__ __forceinline__ float bf2f(bfu h) { return __uint_as_float(((unsigned)h) << 16); }
; __device__ __forceinline__ float silu_f(float x) { return x * __builtin_amdgcn_rcpf(1.f + __expf(-x)); }
; __device__ __forceinline__ void phase_ssd(KP P, char* smem, const int wv) {
;     ...
; #pragma unroll
;         for (int j = 0; j < 4; ++j) {
;           int ii = it * 16 + fqc * 4 + j;
;           float xv = bf2f(xrow[ii]);
;           float y = yacc[j] + __expf(myAc[ii]) * oacc[j] + D_h * xv;
;           float zv = bf2f(sZ[ii * S_LDB + hl * 64 + ps * 16 + frc]);
;           float ygv = y * silu_f(zv);
;           yg[(size_t)(r0 + ii) * DI + head * 64 + ps * 16 + frc] = f2bf(ygv);
;           float sq = ygv * ygv;
;           sq = row16_sum(sq);
;           if (frc == 0) mySq[ii] = sq;
;         }
.Lssd_y_nog1:
	v_add_u32_e32 v103, s3, v101
	v_add_u32_e32 v151, s3, v95
	v_add_u32_e32 v151, 0x20800, v151
	ds_read_b64 v[104:105], v103
	ds_read_u16 v106, v151
	ds_read_u16 v107, v151 offset:272
	ds_read_u16 v108, v151 offset:544
	ds_read_u16 v109, v151 offset:816
	v_add_u32_e32 v110, s50, v96
	v_ashrrev_i32_e32 v111, 31, v110
	s_mov_b64 s[34:35], 0x1000
	v_lshlrev_b64 v[110:111], 12, v[110:111]
	s_nop 0
	v_lshl_add_u64 v[110:111], v[88:89], 0, v[110:111]
	s_waitcnt lgkmcnt(0)
	v_lshlrev_b32_e32 v106, 16, v106
	v_lshlrev_b32_e32 v107, 16, v107
	v_lshlrev_b32_e32 v108, 16, v108
	v_lshlrev_b32_e32 v109, 16, v109
	v_mul_f32_e32 v236, 0xbfb8aa3b, v106
	v_mul_f32_e32 v237, 0xbfb8aa3b, v107
	v_mul_f32_e32 v238, 0xbfb8aa3b, v108
	v_mul_f32_e32 v239, 0xbfb8aa3b, v109
	v_exp_f32_e32 v236, v236
	v_exp_f32_e32 v237, v237
	v_exp_f32_e32 v238, v238
	v_exp_f32_e32 v239, v239
	v_add_f32_e32 v236, 1.0, v236
	v_add_f32_e32 v237, 1.0, v237
	v_add_f32_e32 v238, 1.0, v238
	v_add_f32_e32 v239, 1.0, v239
	v_rcp_f32_e32 v236, v236
	v_rcp_f32_e32 v237, v237
	v_rcp_f32_e32 v238, v238
	v_rcp_f32_e32 v239, v239
	v_lshlrev_b32_e32 v156, 16, v104
	v_and_b32_e32 v157, 0xffff0000, v104
	v_lshlrev_b32_e32 v158, 16, v105
	v_and_b32_e32 v159, 0xffff0000, v105
	v_fma_f32 v84, v84, v154, v80
	v_fma_f32 v85, v85, v155, v81
	v_fma_f32 v86, v86, v90, v82
	v_fma_f32 v87, v87, v91, v83
	v_mul_f32_e32 v156, v150, v156
	v_mul_f32_e32 v157, v150, v157
	v_mul_f32_e32 v158, v150, v158
	v_mul_f32_e32 v159, v150, v159
	v_mul_f32_e32 v236, v236, v106
	v_mul_f32_e32 v237, v237, v107
	v_mul_f32_e32 v238, v238, v108
	v_mul_f32_e32 v239, v239, v109
	v_add_f32_e32 v84, v156, v84
	v_add_f32_e32 v85, v157, v85
	v_add_f32_e32 v86, v158, v86
	v_add_f32_e32 v87, v159, v87
	v_mul_f32_e32 v80, v84, v236
	v_mul_f32_e32 v81, v85, v237
	v_mul_f32_e32 v82, v86, v238
	v_mul_f32_e32 v83, v87, v239
	v_cvt_pk_bf16_f32 v161, v80, v81
	v_cvt_pk_bf16_f32 v163, v82, v83
	v_lshlrev_b32_e32 v160, 16, v161
	v_lshlrev_b32_e32 v162, 16, v163
	v_lshl_add_u64 v[104:105], v[110:111], 0, s[34:35]
	v_mul_f32_e32 v208, v80, v80
	v_mul_f32_e32 v209, v81, v81
	v_mul_f32_e32 v210, v82, v82
	v_mul_f32_e32 v211, v83, v83
	v_lshl_add_u64 v[106:107], v[104:105], 0, s[34:35]
	v_mov_b32_dpp v208, v208 quad_perm:[1,0,3,2] row_mask:0xf bank_mask:0xf bound_ctrl:1
	v_mov_b32_dpp v209, v209 quad_perm:[1,0,3,2] row_mask:0xf bank_mask:0xf bound_ctrl:1
	v_mov_b32_dpp v210, v210 quad_perm:[1,0,3,2] row_mask:0xf bank_mask:0xf bound_ctrl:1
	v_mov_b32_dpp v211, v211 quad_perm:[1,0,3,2] row_mask:0xf bank_mask:0xf bound_ctrl:1
	v_lshl_add_u64 v[108:109], v[106:107], 0, s[34:35]
	v_fmac_f32_e32 v208, v80, v80
	v_fmac_f32_e32 v209, v81, v81
	v_fmac_f32_e32 v210, v82, v82
	v_fmac_f32_e32 v211, v83, v83
	global_store_short_d16_hi v[110:111], v160, off
	global_store_short_d16_hi v[104:105], v161, off
	v_add_f32_dpp v156, v208, v208 quad_perm:[2,3,0,1] row_mask:0xf bank_mask:0xf bound_ctrl:1
	v_add_f32_dpp v157, v209, v209 quad_perm:[2,3,0,1] row_mask:0xf bank_mask:0xf bound_ctrl:1
	v_add_f32_dpp v158, v210, v210 quad_perm:[2,3,0,1] row_mask:0xf bank_mask:0xf bound_ctrl:1
	v_add_f32_dpp v159, v211, v211 quad_perm:[2,3,0,1] row_mask:0xf bank_mask:0xf bound_ctrl:1
	global_store_short_d16_hi v[106:107], v162, off
	global_store_short_d16_hi v[108:109], v163, off
	v_add_f32_dpp v156, v156, v156 row_half_mirror row_mask:0xf bank_mask:0xf bound_ctrl:1
	v_add_f32_dpp v157, v157, v157 row_half_mirror row_mask:0xf bank_mask:0xf bound_ctrl:1
	v_add_f32_dpp v158, v158, v158 row_half_mirror row_mask:0xf bank_mask:0xf bound_ctrl:1
	v_add_f32_dpp v159, v159, v159 row_half_mirror row_mask:0xf bank_mask:0xf bound_ctrl:1
	v_mov_b32_dpp v208, v156 row_mirror row_mask:0xf bank_mask:0xf bound_ctrl:1
	v_mov_b32_dpp v209, v157 row_mirror row_mask:0xf bank_mask:0xf bound_ctrl:1
	v_mov_b32_dpp v210, v158 row_mirror row_mask:0xf bank_mask:0xf bound_ctrl:1
	v_mov_b32_dpp v211, v159 row_mirror row_mask:0xf bank_mask:0xf bound_ctrl:1
	v_add_f32_e32 v156, v156, v208
	v_add_f32_e32 v157, v157, v209
	v_add_f32_e32 v158, v158, v210
	v_add_f32_e32 v159, v159, v211
	s_and_saveexec_b64 s[34:35], vcc
	ds_write_b128 v207, v[156:159] offset:6144
	s_or_b64 exec, exec, s[34:35]
	s_add_i32 s36, s36, 1
	s_add_i32 s50, s50, 16
	v_add_u32_e32 v99, 0x900, v99
	v_add_u32_e32 v100, 0x1100, v100
	v_add_u32_e32 v101, 32, v101
	v_add_u32_e32 v102, 64, v102
	v_add_u32_e32 v95, 0x1100, v95
	s_cmp_eq_u32 s50, 64
	s_cbranch_scc0 .Lssd_y_loop
; __device__ __forceinline__ void phase_ssd(KP P, char* smem, const int wv) {
;     ...
;       {
;         const float dec = __expf(a63);
; #pragma unroll
;         for (int nt = 0; nt < 8; ++nt) hacc[nt] *= dec;
; #pragma unroll
;         for (int ks = 0; ks < 2; ++ks) {
;           const int j0 = ks * 32 + fqc * 8;
;           bf16x8 xr = lds_b128(xrow + j0);
;           f32x4 w0 = *(const f32x4*)(myW + j0), w1 = *(const f32x4*)(myW + j0 + 4);
;           u32x4 xu = __builtin_bit_cast(u32x4, xr);
;           u32x4 pk;
;           pk[0] = cvt_pk_bf16(__uint_as_float(xu[0] << 16) * w0[0], __uint_as_float(xu[0] & 0xffff0000u) * w0[1]);
;           pk[1] = cvt_pk_bf16(__uint_as_float(xu[1] << 16) * w0[2], __uint_as_float(xu[1] & 0xffff0000u) * w0[3]);
;           pk[2] = cvt_pk_bf16(__uint_as_float(xu[2] << 16) * w1[0], __uint_as_float(xu[2] & 0xffff0000u) * w1[1]);
;           pk[3] = cvt_pk_bf16(__uint_as_float(xu[3] << 16) * w1[2], __uint_as_float(xu[3] & 0xffff0000u) * w1[3]);
;           bf16x8 af = __builtin_bit_cast(bf16x8, pk);
; #pragma unroll
;           for (int nt = 0; nt < 8; ++nt) {
;             bf16x8 b = lds_b128(sBT + (nt * 16 + frc) * S_LDT + j0);
;             hacc[nt] = mfma16(af, b, hacc[nt]);
;           }
;         }
.LBB0_441:
	v_mul_f32_e32 v80, s49, v175
	v_exp_f32_e32 v80, v80
	v_lshlrev_b32_e32 v95, 1, v94
	v_lshl_add_u32 v94, v94, 2, s70
	v_add3_u32 v95, s64, v95, v97
	v_pk_mul_f32 v[30:31], v[30:31], v[80:81] op_sel_hi:[1,0]
	v_pk_mul_f32 v[28:29], v[28:29], v[80:81] op_sel_hi:[1,0]
	v_pk_mul_f32 v[34:35], v[34:35], v[80:81] op_sel_hi:[1,0]
	v_pk_mul_f32 v[32:33], v[32:33], v[80:81] op_sel_hi:[1,0]
	v_pk_mul_f32 v[22:23], v[22:23], v[80:81] op_sel_hi:[1,0]
	v_pk_mul_f32 v[20:21], v[20:21], v[80:81] op_sel_hi:[1,0]
	v_pk_mul_f32 v[26:27], v[26:27], v[80:81] op_sel_hi:[1,0]
	v_pk_mul_f32 v[24:25], v[24:25], v[80:81] op_sel_hi:[1,0]
	v_pk_mul_f32 v[14:15], v[14:15], v[80:81] op_sel_hi:[1,0]
	v_pk_mul_f32 v[12:13], v[12:13], v[80:81] op_sel_hi:[1,0]
	v_pk_mul_f32 v[18:19], v[18:19], v[80:81] op_sel_hi:[1,0]
	v_pk_mul_f32 v[16:17], v[16:17], v[80:81] op_sel_hi:[1,0]
	v_pk_mul_f32 v[6:7], v[6:7], v[80:81] op_sel_hi:[1,0]
	v_pk_mul_f32 v[4:5], v[4:5], v[80:81] op_sel_hi:[1,0]
	v_pk_mul_f32 v[10:11], v[10:11], v[80:81] op_sel_hi:[1,0]
	v_pk_mul_f32 v[8:9], v[8:9], v[80:81] op_sel_hi:[1,0]
	ds_read_b128 v[84:87], v94
	ds_read_b128 v[88:91], v94 offset:16
	ds_read_b128 v[104:107], v94 offset:128
	ds_read_b128 v[108:111], v94 offset:144
	ds_read_b128 v[156:159], v95 offset:34816
	ds_read_b128 v[160:163], v95 offset:37120
	ds_read_b128 v[208:211], v95 offset:39424
	ds_read_b128 v[212:215], v95 offset:41728
	ds_read_b128 v[216:219], v95 offset:44032
	ds_read_b128 v[220:223], v95 offset:46336
	ds_read_b128 v[224:227], v95 offset:48640
	ds_read_b128 v[236:239], v95 offset:50944
	s_waitcnt lgkmcnt(8)
	v_lshlrev_b32_e32 v96, 16, v228
	v_and_b32_e32 v97, 0xffff0000, v228
	v_mul_f32_e32 v96, v84, v96
	v_mul_f32_e32 v97, v85, v97
	v_cvt_pk_bf16_f32 v80, v96, v97
	v_lshlrev_b32_e32 v96, 16, v229
	v_and_b32_e32 v97, 0xffff0000, v229
	v_mul_f32_e32 v96, v86, v96
	v_mul_f32_e32 v97, v87, v97
	v_cvt_pk_bf16_f32 v81, v96, v97
	v_lshlrev_b32_e32 v96, 16, v230
	v_and_b32_e32 v97, 0xffff0000, v230
	v_mul_f32_e32 v96, v88, v96
	v_mul_f32_e32 v97, v89, v97
	v_cvt_pk_bf16_f32 v82, v96, v97
	v_lshlrev_b32_e32 v96, 16, v231
	v_and_b32_e32 v97, 0xffff0000, v231
	v_mul_f32_e32 v96, v90, v96
	v_mul_f32_e32 v97, v91, v97
	v_cvt_pk_bf16_f32 v83, v96, v97
	v_lshlrev_b32_e32 v96, 16, v232
	v_and_b32_e32 v97, 0xffff0000, v232
	v_mul_f32_e32 v96, v104, v96
	v_mul_f32_e32 v97, v105, v97
	v_cvt_pk_bf16_f32 v100, v96, v97
	v_lshlrev_b32_e32 v96, 16, v233
	v_and_b32_e32 v97, 0xffff0000, v233
	v_mul_f32_e32 v96, v106, v96
	v_mul_f32_e32 v97, v107, v97
	v_cvt_pk_bf16_f32 v101, v96, v97
	v_lshlrev_b32_e32 v96, 16, v234
	v_and_b32_e32 v97, 0xffff0000, v234
	v_mul_f32_e32 v96, v108, v96
	v_mul_f32_e32 v97, v109, v97
	v_cvt_pk_bf16_f32 v102, v96, v97
	v_lshlrev_b32_e32 v96, 16, v235
	v_and_b32_e32 v97, 0xffff0000, v235
	v_mul_f32_e32 v96, v110, v96
	v_mul_f32_e32 v97, v111, v97
	v_cvt_pk_bf16_f32 v103, v96, v97
	s_waitcnt lgkmcnt(7)
	v_mfma_f32_16x16x32_bf16 v[28:31], v[80:83], v[156:159], v[28:31]
	ds_read_b128 v[156:159], v95 offset:34880
	s_waitcnt lgkmcnt(7)
	v_mfma_f32_16x16x32_bf16 v[32:35], v[80:83], v[160:163], v[32:35]
	ds_read_b128 v[160:163], v95 offset:37184
	s_waitcnt lgkmcnt(7)
	v_mfma_f32_16x16x32_bf16 v[20:23], v[80:83], v[208:211], v[20:23]
	ds_read_b128 v[208:211], v95 offset:39488
	s_waitcnt lgkmcnt(7)
	v_mfma_f32_16x16x32_bf16 v[24:27], v[80:83], v[212:215], v[24:27]
	ds_read_b128 v[212:215], v95 offset:41792
	s_waitcnt lgkmcnt(7)
	v_mfma_f32_16x16x32_bf16 v[12:15], v[80:83], v[216:219], v[12:15]
	ds_read_b128 v[216:219], v95 offset:44096
	s_waitcnt lgkmcnt(7)
	v_mfma_f32_16x16x32_bf16 v[16:19], v[80:83], v[220:223], v[16:19]
	ds_read_b128 v[220:223], v95 offset:46400
	s_waitcnt lgkmcnt(7)
	v_mfma_f32_16x16x32_bf16 v[4:7], v[80:83], v[224:227], v[4:7]
	ds_read_b128 v[224:227], v95 offset:48704
	s_waitcnt lgkmcnt(7)
; __device__ __forceinline__ void phase_ssd(KP P, char* smem, const int wv) {
;     ...
;           for (int nt = 0; nt < 8; ++nt) {
;             bf16x8 b = lds_b128(sBT + (nt * 16 + frc) * S_LDT + j0);
;             hacc[nt] = mfma16(af, b, hacc[nt]);
;           }
;         }
; #pragma unroll
;         for (int nt = 0; nt < 8; ++nt)
; #pragma unroll
;           for (int j = 0; j < 4; ++j) myH[(fqc * 4 + j) * S_LDB + nt * 16 + frc] = f2bf(hacc[nt][j]);
;       }
;       lds_barrier();
;       if (tid < 64) {
;         float sm = 0.f;
; #pragma unroll
;         for (int ww = 0; ww < 8; ++ww) sm += sSq[ww * 64 + tid];
;         ssqp[(size_t)(r0 + tid) * 16 + g * 4 + hp] = sm;
;       }
	v_mfma_f32_16x16x32_bf16 v[8:11], v[80:83], v[236:239], v[8:11]
	ds_read_b128 v[236:239], v95 offset:51008
	s_waitcnt lgkmcnt(7)
	v_mfma_f32_16x16x32_bf16 v[28:31], v[100:103], v[156:159], v[28:31]
	s_waitcnt lgkmcnt(6)
	v_mfma_f32_16x16x32_bf16 v[32:35], v[100:103], v[160:163], v[32:35]
	s_waitcnt lgkmcnt(5)
	v_mfma_f32_16x16x32_bf16 v[20:23], v[100:103], v[208:211], v[20:23]
	s_waitcnt lgkmcnt(4)
	v_mfma_f32_16x16x32_bf16 v[24:27], v[100:103], v[212:215], v[24:27]
	s_waitcnt lgkmcnt(3)
	v_mfma_f32_16x16x32_bf16 v[12:15], v[100:103], v[216:219], v[12:15]
	s_waitcnt lgkmcnt(2)
	v_mfma_f32_16x16x32_bf16 v[16:19], v[100:103], v[220:223], v[16:19]
	s_waitcnt lgkmcnt(1)
	v_mfma_f32_16x16x32_bf16 v[4:7], v[100:103], v[224:227], v[4:7]
	s_waitcnt lgkmcnt(0)
	v_mfma_f32_16x16x32_bf16 v[8:11], v[100:103], v[236:239], v[8:11]
	v_lshlrev_b32_e32 v81, 1, v92
	v_add3_u32 v0, s9, v81, v0
	v_cvt_pk_bf16_f32 v80, v28, v29
	v_lshlrev_b32_e32 v81, 16, v80
	ds_write_b16_d16_hi v0, v80 offset:272
	ds_write_b16_d16_hi v0, v81
	v_cvt_pk_bf16_f32 v80, v30, v31
	v_lshlrev_b32_e32 v81, 16, v80
	ds_write_b16_d16_hi v0, v80 offset:816
	ds_write_b16_d16_hi v0, v81 offset:544
	v_cvt_pk_bf16_f32 v80, v32, v33
	v_lshlrev_b32_e32 v81, 16, v80
	ds_write_b16_d16_hi v0, v80 offset:304
	ds_write_b16_d16_hi v0, v81 offset:32
	v_cvt_pk_bf16_f32 v80, v34, v35
	v_lshlrev_b32_e32 v81, 16, v80
	ds_write_b16_d16_hi v0, v80 offset:848
	ds_write_b16_d16_hi v0, v81 offset:576
	v_cvt_pk_bf16_f32 v80, v20, v21
	v_lshlrev_b32_e32 v81, 16, v80
	ds_write_b16_d16_hi v0, v80 offset:336
	ds_write_b16_d16_hi v0, v81 offset:64
	v_cvt_pk_bf16_f32 v80, v22, v23
	v_lshlrev_b32_e32 v81, 16, v80
	ds_write_b16_d16_hi v0, v80 offset:880
	ds_write_b16_d16_hi v0, v81 offset:608
	v_cvt_pk_bf16_f32 v80, v24, v25
	v_lshlrev_b32_e32 v81, 16, v80
	ds_write_b16_d16_hi v0, v80 offset:368
	ds_write_b16_d16_hi v0, v81 offset:96
	v_cvt_pk_bf16_f32 v80, v26, v27
	v_lshlrev_b32_e32 v81, 16, v80
	ds_write_b16_d16_hi v0, v80 offset:912
	ds_write_b16_d16_hi v0, v81 offset:640
	v_cvt_pk_bf16_f32 v80, v12, v13
	v_lshlrev_b32_e32 v81, 16, v80
	ds_write_b16_d16_hi v0, v80 offset:400
	ds_write_b16_d16_hi v0, v81 offset:128
	v_cvt_pk_bf16_f32 v80, v14, v15
	v_lshlrev_b32_e32 v81, 16, v80
	ds_write_b16_d16_hi v0, v80 offset:944
	ds_write_b16_d16_hi v0, v81 offset:672
	v_cvt_pk_bf16_f32 v80, v16, v17
	v_lshlrev_b32_e32 v81, 16, v80
	ds_write_b16_d16_hi v0, v80 offset:432
	ds_write_b16_d16_hi v0, v81 offset:160
	v_cvt_pk_bf16_f32 v80, v18, v19
	v_lshlrev_b32_e32 v81, 16, v80
	ds_write_b16_d16_hi v0, v80 offset:976
	ds_write_b16_d16_hi v0, v81 offset:704
	v_cvt_pk_bf16_f32 v80, v4, v5
	v_lshlrev_b32_e32 v81, 16, v80
	ds_write_b16_d16_hi v0, v80 offset:464
	ds_write_b16_d16_hi v0, v81 offset:192
	v_cvt_pk_bf16_f32 v80, v6, v7
	v_lshlrev_b32_e32 v81, 16, v80
	ds_write_b16_d16_hi v0, v80 offset:1008
	ds_write_b16_d16_hi v0, v81 offset:736
	v_cvt_pk_bf16_f32 v80, v8, v9
	v_lshlrev_b32_e32 v81, 16, v80
	ds_write_b16_d16_hi v0, v80 offset:496
	ds_write_b16_d16_hi v0, v81 offset:224
	v_cvt_pk_bf16_f32 v80, v10, v11
	v_lshlrev_b32_e32 v81, 16, v80
	ds_write_b16_d16_hi v0, v80 offset:1040
	ds_write_b16_d16_hi v0, v81 offset:768
	s_waitcnt lgkmcnt(0)
	s_barrier
	s_and_saveexec_b64 s[34:35], s[14:15]
	s_cbranch_execz .LBB0_414
	ds_read2st64_b32 v[80:81], v204 offset1:1
	ds_read2st64_b32 v[82:83], v204 offset0:2 offset1:3
	ds_read2st64_b32 v[84:85], v204 offset0:4 offset1:5
	ds_read2st64_b32 v[86:87], v204 offset0:6 offset1:7
	v_add_u32_e32 v88, s48, v113
	v_ashrrev_i32_e32 v89, 31, v88
	v_lshlrev_b64 v[88:89], 6, v[88:89]
	v_lshl_add_u64 v[88:89], s[80:81], 0, v[88:89]
	s_waitcnt lgkmcnt(0)
	v_add_f32_e32 v0, 0, v80
	v_add_f32_e32 v0, v0, v81
	v_add_f32_e32 v0, v0, v82
	v_add_f32_e32 v0, v0, v83
	v_add_f32_e32 v0, v0, v84
	v_add_f32_e32 v0, v0, v85
	v_add_f32_e32 v0, v0, v86
	v_add_f32_e32 v0, v0, v87
	global_store_dword v[88:89], v0, off
	s_branch .LBB0_414
